# GEMM tile scheduler: the division by the group size (always 8) replaced by shift and mask in the swiglu and proj unit loops (34 -> 6 scalar/vector instructions per tile, no VALU round trip)
# speedup vs baseline: 1.0054x; 1.0002x over previous
;     __host__ __device__ bool next(int i, Unit& u) const {
;         const long L = (long)i * G + c; if (L >= nwg) return false;
;         int wgid = (int)L; { const int q = nwg / NXCD, r = nwg % NXCD, xcd = wgid % NXCD, off = wgid / NXCD; wgid = (xcd < r ? xcd * (q + 1) : r * (q + 1) + (xcd - r) * q) + off; }
;         const int nig = WGM * nN, gid = wgid / nig, fm = gid * WGM, gsz = (nM - fm) < WGM ? (nM - fm) : WGM;
;         u.pm = fm + ((wgid % nig) % gsz); u.pn = (wgid % nig) / gsz; return true;
.LBB0_138:
	s_add_i32 s44, s44, 1
	s_mul_i32 s10, s44, s43
	s_mul_hi_u32 s11, s44, s70
	s_add_i32 s11, s11, s10
	s_mul_i32 s10, s44, s70
	s_add_u32 s24, s10, s6
	s_addc_u32 s25, s11, s38
	v_cmp_gt_i64_e32 vcc, s[24:25], v[198:199]
	v_cmp_lt_i64_e64 s[10:11], s[24:25], v[196:197]
	s_cbranch_vccnz .LBB0_140
	s_ashr_i32 s20, s24, 31
	s_lshr_b32 s20, s20, 29
	s_add_i32 s20, s24, s20
	s_ashr_i32 s21, s20, 3
	s_and_b32 s20, s20, -8
	s_sub_i32 s20, s24, s20
	s_cmp_lt_i32 s20, 0
	s_cselect_b32 s22, s3, 0x1a0
	s_mul_i32 s20, s20, s22
	s_add_i32 s20, s20, s21
	s_mul_hi_i32 s21, s20, 0x4ec4ec4f
	s_lshr_b32 s22, s21, 31
	s_ashr_i32 s21, s21, 5
	s_add_i32 s21, s21, s22
	s_lshl_b32 s22, s21, 3
	s_mulk_i32 s21, 0x68
	s_sub_i32 s21, s20, s21
	s_lshr_b32 s20, s21, 3
	s_and_b32 s21, s21, 7
	s_add_i32 s22, s22, s21

;     __host__ __device__ bool next(int i, Unit& u) const {
;         const long L = (long)i * G + c; if (L >= nwg) return false;
;         int wgid = (int)L; { const int q = nwg / NXCD, r = nwg % NXCD, xcd = wgid % NXCD, off = wgid / NXCD; wgid = (xcd < r ? xcd * (q + 1) : r * (q + 1) + (xcd - r) * q) + off; }
;         const int nig = WGM * nN, gid = wgid / nig, fm = gid * WGM, gsz = (nM - fm) < WGM ? (nM - fm) : WGM;
;         u.pm = fm + ((wgid % nig) % gsz); u.pn = (wgid % nig) / gsz; return true;
.LBB0_781:
	s_add_i32 s43, s43, 1
	s_mul_i32 s10, s43, s42
	s_mul_hi_u32 s11, s43, s70
	s_add_i32 s11, s11, s10
	s_mul_i32 s10, s43, s70
	s_add_u32 s20, s10, s6
	s_addc_u32 s21, s11, s35
	v_cmp_gt_i64_e32 vcc, s[20:21], v[208:209]
	v_cmp_lt_i64_e64 s[10:11], s[20:21], v[206:207]
	s_cbranch_vccnz .LBB0_783
	s_ashr_i32 s16, s20, 31
	s_lshr_b32 s16, s16, 29
	s_add_i32 s16, s20, s16
	s_ashr_i32 s17, s16, 3
	s_and_b32 s16, s16, -8
	s_sub_i32 s16, s20, s16
	s_cmp_lt_i32 s16, 0
	s_cselect_b32 s18, s3, 0x2c0
	s_mul_i32 s16, s16, s18
	s_add_i32 s16, s16, s17
	s_mul_hi_i32 s17, s16, 0x2e8ba2e9
	s_lshr_b32 s18, s17, 31
	s_ashr_i32 s17, s17, 5
	s_add_i32 s17, s17, s18
	s_lshl_b32 s18, s17, 3
	s_mulk_i32 s17, 0xb0
	s_sub_i32 s17, s16, s17
	s_lshr_b32 s16, s17, 3
	s_and_b32 s17, s17, 7
	s_add_i32 s18, s18, s17
